# v31: v28 + OUT-GEMM epilogue stores write-through (sc0 sc1) so the phase-6 barrier has no L2 write-back to do
# speedup vs baseline: 1.0017x; 1.0017x over previous
.LBB0_1425:
	v_mov_b32_e32 v64, v166
	s_waitcnt lgkmcnt(0)
	s_barrier
	v_add_u32_e32 v65, s5, v138
	v_and_b32_e32 v66, 31, v64
	v_lshrrev_b32_e32 v64, 3, v64
	v_and_or_b32 v86, v64, 4, v65
	s_lshl_b32 s26, s3, 2
	v_lshl_add_u64 v[64:65], v[130:131], 0, s[26:27]
	v_lshlrev_b32_e32 v128, 2, v66
	v_ashrrev_i32_e32 v87, 31, v86
	v_or_b32_e32 v66, 1, v86
	v_or_b32_e32 v68, 2, v86
	v_or_b32_e32 v70, 3, v86
	v_or_b32_e32 v72, 8, v86
	v_or_b32_e32 v74, 9, v86
	v_or_b32_e32 v76, 10, v86
	v_or_b32_e32 v78, 11, v86
	v_or_b32_e32 v80, 16, v86
	v_or_b32_e32 v82, 17, v86
	v_or_b32_e32 v84, 18, v86
	v_or_b32_e32 v88, 19, v86
	v_or_b32_e32 v92, 24, v86
	v_or_b32_e32 v94, 25, v86
	v_or_b32_e32 v96, 26, v86
	v_or_b32_e32 v134, 27, v86
	v_lshl_add_u64 v[90:91], v[64:65], 0, v[128:129]
	v_lshlrev_b64 v[64:65], 12, v[86:87]
	v_ashrrev_i32_e32 v67, 31, v66
	v_ashrrev_i32_e32 v69, 31, v68
	v_ashrrev_i32_e32 v71, 31, v70
	v_ashrrev_i32_e32 v73, 31, v72
	v_ashrrev_i32_e32 v75, 31, v74
	v_ashrrev_i32_e32 v77, 31, v76
	v_ashrrev_i32_e32 v79, 31, v78
	v_ashrrev_i32_e32 v81, 31, v80
	v_ashrrev_i32_e32 v83, 31, v82
	v_ashrrev_i32_e32 v85, 31, v84
	v_ashrrev_i32_e32 v89, 31, v88
	v_ashrrev_i32_e32 v93, 31, v92
	v_ashrrev_i32_e32 v95, 31, v94
	v_ashrrev_i32_e32 v97, 31, v96
	v_ashrrev_i32_e32 v135, 31, v134
	v_lshl_add_u64 v[98:99], v[90:91], 0, v[64:65]
	v_lshlrev_b64 v[66:67], 12, v[66:67]
	v_lshlrev_b64 v[68:69], 12, v[68:69]
	v_lshlrev_b64 v[70:71], 12, v[70:71]
	v_lshlrev_b64 v[72:73], 12, v[72:73]
	v_lshlrev_b64 v[74:75], 12, v[74:75]
	v_lshlrev_b64 v[76:77], 12, v[76:77]
	v_lshlrev_b64 v[78:79], 12, v[78:79]
	v_lshlrev_b64 v[80:81], 12, v[80:81]
	v_lshlrev_b64 v[82:83], 12, v[82:83]
	v_lshlrev_b64 v[84:85], 12, v[84:85]
	v_lshlrev_b64 v[88:89], 12, v[88:89]
	v_lshlrev_b64 v[92:93], 12, v[92:93]
	v_lshlrev_b64 v[94:95], 12, v[94:95]
	v_lshlrev_b64 v[96:97], 12, v[96:97]
	v_lshlrev_b64 v[134:135], 12, v[134:135]
	v_lshl_add_u64 v[100:101], v[90:91], 0, v[66:67]
	v_lshl_add_u64 v[102:103], v[90:91], 0, v[68:69]
	v_lshl_add_u64 v[104:105], v[90:91], 0, v[70:71]
	v_lshl_add_u64 v[106:107], v[90:91], 0, v[72:73]
	v_lshl_add_u64 v[108:109], v[90:91], 0, v[74:75]
	v_lshl_add_u64 v[110:111], v[90:91], 0, v[76:77]
	v_lshl_add_u64 v[112:113], v[90:91], 0, v[78:79]
	v_lshl_add_u64 v[114:115], v[90:91], 0, v[80:81]
	v_lshl_add_u64 v[116:117], v[90:91], 0, v[82:83]
	v_lshl_add_u64 v[118:119], v[90:91], 0, v[84:85]
	v_lshl_add_u64 v[120:121], v[90:91], 0, v[88:89]
	v_lshl_add_u64 v[122:123], v[90:91], 0, v[92:93]
	v_lshl_add_u64 v[124:125], v[90:91], 0, v[94:95]
	v_lshl_add_u64 v[126:127], v[90:91], 0, v[96:97]
	v_lshl_add_u64 v[162:163], v[90:91], 0, v[134:135]
	global_load_dword v161, v[98:99], off
	global_load_dword v167, v[100:101], off
	global_load_dword v194, v[102:103], off
	global_load_dword v195, v[104:105], off
	global_load_dword v196, v[104:105], off offset:128
	global_load_dword v197, v[102:103], off offset:128
	global_load_dword v198, v[100:101], off offset:128
	global_load_dword v199, v[98:99], off offset:128
	global_load_dword v200, v[106:107], off
	global_load_dword v201, v[108:109], off
	global_load_dword v202, v[110:111], off
	global_load_dword v203, v[112:113], off
	global_load_dword v204, v[112:113], off offset:128
	global_load_dword v205, v[110:111], off offset:128
	global_load_dword v206, v[108:109], off offset:128
	global_load_dword v207, v[106:107], off offset:128
	global_load_dword v208, v[114:115], off
	global_load_dword v209, v[116:117], off
	global_load_dword v210, v[118:119], off
	global_load_dword v211, v[120:121], off
	global_load_dword v212, v[120:121], off offset:128
	global_load_dword v213, v[118:119], off offset:128
	global_load_dword v214, v[116:117], off offset:128
	global_load_dword v215, v[114:115], off offset:128
	global_load_dword v216, v[122:123], off
	global_load_dword v217, v[124:125], off
	global_load_dword v218, v[126:127], off
	global_load_dword v219, v[162:163], off
	global_load_dword v220, v[162:163], off offset:128
	global_load_dword v221, v[126:127], off offset:128
	global_load_dword v222, v[124:125], off offset:128
	global_load_dword v223, v[122:123], off offset:128
	v_or_b32_e32 v98, 32, v86
	v_or_b32_e32 v102, 33, v86
	v_or_b32_e32 v106, 34, v86
	v_or_b32_e32 v110, 35, v86
	v_or_b32_e32 v114, 40, v86
	v_or_b32_e32 v118, 41, v86
	v_or_b32_e32 v122, 42, v86
	v_or_b32_e32 v126, 43, v86
	v_or_b32_e32 v164, 48, v86
	v_or_b32_e32 v170, 49, v86
	v_or_b32_e32 v174, 50, v86
	v_or_b32_e32 v178, 51, v86
	v_or_b32_e32 v182, 56, v86
	v_or_b32_e32 v186, 57, v86
	v_or_b32_e32 v190, 58, v86
	v_ashrrev_i32_e32 v99, 31, v98
	v_ashrrev_i32_e32 v103, 31, v102
	v_ashrrev_i32_e32 v107, 31, v106
	v_ashrrev_i32_e32 v111, 31, v110
	v_ashrrev_i32_e32 v115, 31, v114
	v_ashrrev_i32_e32 v119, 31, v118
	v_ashrrev_i32_e32 v123, 31, v122
	v_ashrrev_i32_e32 v127, 31, v126
	v_ashrrev_i32_e32 v165, 31, v164
	v_ashrrev_i32_e32 v171, 31, v170
	v_ashrrev_i32_e32 v175, 31, v174
	v_ashrrev_i32_e32 v179, 31, v178
	v_ashrrev_i32_e32 v183, 31, v182
	v_ashrrev_i32_e32 v187, 31, v186
	v_ashrrev_i32_e32 v191, 31, v190
	v_or_b32_e32 v86, 59, v86
	v_lshlrev_b64 v[98:99], 12, v[98:99]
	v_lshlrev_b64 v[102:103], 12, v[102:103]
	v_lshlrev_b64 v[106:107], 12, v[106:107]
	v_lshlrev_b64 v[110:111], 12, v[110:111]
	v_lshlrev_b64 v[114:115], 12, v[114:115]
	v_lshlrev_b64 v[118:119], 12, v[118:119]
	v_lshlrev_b64 v[122:123], 12, v[122:123]
	v_lshlrev_b64 v[126:127], 12, v[126:127]
	v_lshlrev_b64 v[164:165], 12, v[164:165]
	v_lshlrev_b64 v[170:171], 12, v[170:171]
	v_lshlrev_b64 v[174:175], 12, v[174:175]
	v_lshlrev_b64 v[178:179], 12, v[178:179]
	v_lshlrev_b64 v[182:183], 12, v[182:183]
	v_lshlrev_b64 v[186:187], 12, v[186:187]
	v_lshlrev_b64 v[190:191], 12, v[190:191]
	v_ashrrev_i32_e32 v87, 31, v86
	v_lshl_add_u64 v[100:101], v[90:91], 0, v[98:99]
	v_lshl_add_u64 v[104:105], v[90:91], 0, v[102:103]
	v_lshl_add_u64 v[108:109], v[90:91], 0, v[106:107]
	v_lshl_add_u64 v[112:113], v[90:91], 0, v[110:111]
	v_lshl_add_u64 v[116:117], v[90:91], 0, v[114:115]
	v_lshl_add_u64 v[120:121], v[90:91], 0, v[118:119]
	v_lshl_add_u64 v[124:125], v[90:91], 0, v[122:123]
	v_lshl_add_u64 v[162:163], v[90:91], 0, v[126:127]
	v_lshl_add_u64 v[168:169], v[90:91], 0, v[164:165]
	v_lshl_add_u64 v[172:173], v[90:91], 0, v[170:171]
	v_lshl_add_u64 v[176:177], v[90:91], 0, v[174:175]
	v_lshl_add_u64 v[180:181], v[90:91], 0, v[178:179]
	v_lshl_add_u64 v[184:185], v[90:91], 0, v[182:183]
	v_lshl_add_u64 v[188:189], v[90:91], 0, v[186:187]
	v_lshl_add_u64 v[192:193], v[90:91], 0, v[190:191]
	v_lshlrev_b64 v[86:87], 12, v[86:87]
	v_lshl_add_u64 v[90:91], v[90:91], 0, v[86:87]
	global_load_dword v224, v[100:101], off
	global_load_dword v225, v[104:105], off
	global_load_dword v226, v[108:109], off
	global_load_dword v227, v[112:113], off
	s_nop 0
	global_load_dword v112, v[112:113], off offset:128
	s_nop 0
	global_load_dword v108, v[108:109], off offset:128
	s_nop 0
	global_load_dword v104, v[104:105], off offset:128
	s_nop 0
	global_load_dword v100, v[100:101], off offset:128
	s_nop 0
	global_load_dword v101, v[116:117], off
	global_load_dword v105, v[120:121], off
	global_load_dword v109, v[124:125], off
	global_load_dword v113, v[162:163], off
	s_nop 0
	global_load_dword v162, v[162:163], off offset:128
	s_nop 0
	global_load_dword v124, v[124:125], off offset:128
	s_nop 0
	global_load_dword v120, v[120:121], off offset:128
	s_nop 0
	global_load_dword v116, v[116:117], off offset:128
	s_nop 0
	global_load_dword v117, v[168:169], off
	global_load_dword v121, v[172:173], off
	global_load_dword v125, v[176:177], off
	global_load_dword v163, v[180:181], off
	s_nop 0
	global_load_dword v180, v[180:181], off offset:128
	s_nop 0
	global_load_dword v176, v[176:177], off offset:128
	s_nop 0
	global_load_dword v172, v[172:173], off offset:128
	s_nop 0
	global_load_dword v168, v[168:169], off offset:128
	s_nop 0
	global_load_dword v169, v[184:185], off
	global_load_dword v173, v[188:189], off
	global_load_dword v177, v[192:193], off
	global_load_dword v181, v[90:91], off
	global_load_dword v228, v[90:91], off offset:128
	s_nop 0
	global_load_dword v192, v[192:193], off offset:128
	s_nop 0
	global_load_dword v188, v[188:189], off offset:128
	s_nop 0
	global_load_dword v184, v[184:185], off offset:128
	v_lshl_add_u64 v[90:91], v[132:133], 0, s[26:27]
	v_lshl_add_u64 v[90:91], v[90:91], 0, v[128:129]
	s_waitcnt vmcnt(0)
	v_add_f32_e32 v48, v48, v161
	v_lshl_add_u64 v[64:65], v[90:91], 0, v[64:65]
	v_add_f32_e32 v32, v32, v199
	global_store_dword v[64:65], v48, off sc0 sc1
	v_add_f32_e32 v128, v49, v167
	v_lshl_add_u64 v[48:49], v[90:91], 0, v[66:67]
	global_store_dword v[64:65], v32, off offset:128 sc0 sc1
	v_add_f32_e32 v32, v33, v198
	v_add_f32_e32 v50, v50, v194
	v_lshl_add_u64 v[66:67], v[90:91], 0, v[68:69]
	global_store_dword v[48:49], v32, off offset:128 sc0 sc1
	v_add_f32_e32 v32, v34, v197
	global_store_dword v[66:67], v50, off sc0 sc1
	v_add_f32_e32 v68, v51, v195
	v_lshl_add_u64 v[50:51], v[90:91], 0, v[70:71]
	global_store_dword v[66:67], v32, off offset:128 sc0 sc1
	v_add_f32_e32 v32, v35, v196
	global_store_dword v[50:51], v68, off sc0 sc1
	v_add_f32_e32 v52, v52, v200
	v_lshl_add_u64 v[68:69], v[90:91], 0, v[72:73]
	global_store_dword v[50:51], v32, off offset:128 sc0 sc1
	v_add_f32_e32 v32, v36, v207
	global_store_dword v[68:69], v52, off sc0 sc1
	v_add_f32_e32 v70, v53, v201
	v_lshl_add_u64 v[52:53], v[90:91], 0, v[74:75]
	global_store_dword v[68:69], v32, off offset:128 sc0 sc1
	v_add_f32_e32 v32, v37, v206
	global_store_dword v[52:53], v70, off sc0 sc1
	v_add_f32_e32 v54, v54, v202
	v_lshl_add_u64 v[70:71], v[90:91], 0, v[76:77]
	global_store_dword v[52:53], v32, off offset:128 sc0 sc1
	v_add_f32_e32 v32, v38, v205
	global_store_dword v[70:71], v54, off sc0 sc1
	v_add_f32_e32 v72, v55, v203
	v_lshl_add_u64 v[54:55], v[90:91], 0, v[78:79]
	global_store_dword v[70:71], v32, off offset:128 sc0 sc1
	v_add_f32_e32 v32, v39, v204
	global_store_dword v[54:55], v72, off sc0 sc1
	v_add_f32_e32 v56, v56, v208
	v_lshl_add_u64 v[72:73], v[90:91], 0, v[80:81]
	global_store_dword v[54:55], v32, off offset:128 sc0 sc1
	v_add_f32_e32 v32, v40, v215
	global_store_dword v[72:73], v56, off sc0 sc1
	v_add_f32_e32 v74, v57, v209
	v_lshl_add_u64 v[56:57], v[90:91], 0, v[82:83]
	global_store_dword v[72:73], v32, off offset:128 sc0 sc1
	v_add_f32_e32 v32, v41, v214
	global_store_dword v[56:57], v74, off sc0 sc1
	v_add_f32_e32 v58, v58, v210
	v_lshl_add_u64 v[74:75], v[90:91], 0, v[84:85]
	global_store_dword v[56:57], v32, off offset:128 sc0 sc1
	v_add_f32_e32 v32, v42, v213
	global_store_dword v[74:75], v58, off sc0 sc1
	v_add_f32_e32 v76, v59, v211
	v_lshl_add_u64 v[58:59], v[90:91], 0, v[88:89]
	global_store_dword v[74:75], v32, off offset:128 sc0 sc1
	v_add_f32_e32 v32, v43, v212
	global_store_dword v[58:59], v76, off sc0 sc1
	v_add_f32_e32 v60, v60, v216
	v_lshl_add_u64 v[76:77], v[90:91], 0, v[92:93]
	global_store_dword v[58:59], v32, off offset:128 sc0 sc1
	v_add_f32_e32 v32, v44, v223
	global_store_dword v[76:77], v60, off sc0 sc1
	v_add_f32_e32 v78, v61, v217
	v_lshl_add_u64 v[60:61], v[90:91], 0, v[94:95]
	global_store_dword v[76:77], v32, off offset:128 sc0 sc1
	v_add_f32_e32 v32, v45, v222
	global_store_dword v[60:61], v78, off sc0 sc1
	v_add_f32_e32 v62, v62, v218
	v_lshl_add_u64 v[78:79], v[90:91], 0, v[96:97]
	global_store_dword v[60:61], v32, off offset:128 sc0 sc1
	v_add_f32_e32 v32, v46, v221
	global_store_dword v[78:79], v62, off sc0 sc1
	v_add_f32_e32 v80, v63, v219
	v_lshl_add_u64 v[62:63], v[90:91], 0, v[134:135]
	global_store_dword v[78:79], v32, off offset:128 sc0 sc1
	v_add_f32_e32 v32, v47, v220
	global_store_dword v[62:63], v32, off offset:128 sc0 sc1
	v_add_f32_e32 v16, v16, v224
	v_lshl_add_u64 v[32:33], v[90:91], 0, v[98:99]
	v_add_f32_e32 v0, v0, v100
	global_store_dword v[32:33], v16, off sc0 sc1
	v_add_f32_e32 v34, v17, v225
	v_lshl_add_u64 v[16:17], v[90:91], 0, v[102:103]
	global_store_dword v[32:33], v0, off offset:128 sc0 sc1
	v_add_f32_e32 v0, v1, v104
	global_store_dword v[16:17], v34, off sc0 sc1
	v_add_f32_e32 v18, v18, v226
	v_lshl_add_u64 v[34:35], v[90:91], 0, v[106:107]
	global_store_dword v[16:17], v0, off offset:128 sc0 sc1
	v_add_f32_e32 v0, v2, v108
	global_store_dword v[34:35], v18, off sc0 sc1
	v_add_f32_e32 v36, v19, v227
	v_lshl_add_u64 v[18:19], v[90:91], 0, v[110:111]
	global_store_dword v[34:35], v0, off offset:128 sc0 sc1
	v_add_f32_e32 v0, v3, v112
	global_store_dword v[18:19], v36, off sc0 sc1
	v_add_f32_e32 v20, v20, v101
	v_lshl_add_u64 v[36:37], v[90:91], 0, v[114:115]
	global_store_dword v[18:19], v0, off offset:128 sc0 sc1
	v_add_f32_e32 v0, v4, v116
	global_store_dword v[36:37], v20, off sc0 sc1
	v_add_f32_e32 v38, v21, v105
	v_lshl_add_u64 v[20:21], v[90:91], 0, v[118:119]
	global_store_dword v[36:37], v0, off offset:128 sc0 sc1
	v_add_f32_e32 v0, v5, v120
	global_store_dword v[20:21], v38, off sc0 sc1
	v_add_f32_e32 v22, v22, v109
	v_lshl_add_u64 v[38:39], v[90:91], 0, v[122:123]
	global_store_dword v[20:21], v0, off offset:128 sc0 sc1
	v_add_f32_e32 v0, v6, v124
	global_store_dword v[38:39], v22, off sc0 sc1
	v_add_f32_e32 v40, v23, v113
	v_lshl_add_u64 v[22:23], v[90:91], 0, v[126:127]
	global_store_dword v[38:39], v0, off offset:128 sc0 sc1
	v_add_f32_e32 v0, v7, v162
	global_store_dword v[22:23], v40, off sc0 sc1
	v_add_f32_e32 v24, v24, v117
	v_lshl_add_u64 v[40:41], v[90:91], 0, v[164:165]
	global_store_dword v[22:23], v0, off offset:128 sc0 sc1
	v_add_f32_e32 v0, v8, v168
	global_store_dword v[40:41], v24, off sc0 sc1
	v_add_f32_e32 v42, v25, v121
	v_lshl_add_u64 v[24:25], v[90:91], 0, v[170:171]
	global_store_dword v[40:41], v0, off offset:128 sc0 sc1
	v_add_f32_e32 v0, v9, v172
	global_store_dword v[24:25], v42, off sc0 sc1
	v_add_f32_e32 v26, v26, v125
	v_lshl_add_u64 v[42:43], v[90:91], 0, v[174:175]
	global_store_dword v[24:25], v0, off offset:128 sc0 sc1
	v_add_f32_e32 v0, v10, v176
	global_store_dword v[42:43], v26, off sc0 sc1
	v_add_f32_e32 v44, v27, v163
	v_lshl_add_u64 v[26:27], v[90:91], 0, v[178:179]
	global_store_dword v[42:43], v0, off offset:128 sc0 sc1
	v_add_f32_e32 v0, v11, v180
	global_store_dword v[26:27], v44, off sc0 sc1
	v_add_f32_e32 v28, v28, v169
	v_lshl_add_u64 v[44:45], v[90:91], 0, v[182:183]
	global_store_dword v[26:27], v0, off offset:128 sc0 sc1
	v_add_f32_e32 v0, v12, v184
	global_store_dword v[44:45], v28, off sc0 sc1
	v_add_f32_e32 v46, v29, v173
	v_lshl_add_u64 v[28:29], v[90:91], 0, v[186:187]
	global_store_dword v[44:45], v0, off offset:128 sc0 sc1
	v_add_f32_e32 v0, v13, v188
	global_store_dword v[28:29], v46, off sc0 sc1
	v_add_f32_e32 v30, v30, v177
	v_lshl_add_u64 v[46:47], v[90:91], 0, v[190:191]
	global_store_dword v[28:29], v0, off offset:128 sc0 sc1
	v_add_f32_e32 v0, v14, v192
	s_add_i32 s38, s38, s37
	s_add_i32 s0, s0, s1
	global_store_dword v[48:49], v128, off sc0 sc1
	global_store_dword v[46:47], v30, off sc0 sc1
	v_add_f32_e32 v48, v31, v181
	v_lshl_add_u64 v[30:31], v[90:91], 0, v[86:87]
	global_store_dword v[46:47], v0, off offset:128 sc0 sc1
	v_add_f32_e32 v0, v15, v228
	s_cmpk_lt_i32 s38, 0x400
	global_store_dword v[62:63], v80, off sc0 sc1
	global_store_dword v[30:31], v48, off sc0 sc1
	global_store_dword v[30:31], v0, off offset:128 sc0 sc1
	s_waitcnt lgkmcnt(0)
	s_barrier
	s_cbranch_scc0 .LBB0_1456
